# FFN-out residual epilogue rewritten: in-place unpack+fma, no +0 adds, f32 sum of squares via packed fma (unrounded values, wider than before), permlane16/32 swaps instead of ds_bpermute, per-group vmc
# baseline (speedup 1.0000x reference)
.LBB0_274:
	v_mbcnt_lo_u32_b32 v94, -1, 0
	v_mbcnt_hi_u32_b32 v94, -1, v94
	s_lshl_b32 s9, s25, 8
	v_ashrrev_i32_e32 v95, 1, v94
	s_lshl_b32 s7, s26, 8
	s_or_b32 s9, s9, s59
	v_and_b32_e32 v95, -8, v95
	s_add_i32 s7, s7, s58
	v_add_u32_e32 v204, s9, v95
	v_ashrrev_i32_e32 v205, 31, v204
	v_and_or_b32 v234, v94, 15, s7
	v_lshlrev_b64 v[236:237], 1, v[204:205]
	v_ashrrev_i32_e32 v235, 31, v234
	v_cmp_gt_u32_e32 vcc, 16, v94
	v_lshl_add_u64 v[94:95], s[42:43], 0, v[236:237]
	v_lshlrev_b64 v[238:239], 11, v[234:235]
	v_lshl_add_u64 v[96:97], v[94:95], 0, v[238:239]
	global_load_dwordx4 v[190:193], v[96:97], off
	global_load_dwordx4 v[186:189], v[96:97], off offset:256
	v_or_b32_e32 v230, 16, v234
	v_ashrrev_i32_e32 v231, 31, v230
	v_or_b32_e32 v210, 32, v234
	v_lshlrev_b64 v[232:233], 11, v[230:231]
	v_ashrrev_i32_e32 v211, 31, v210
	v_or_b32_e32 v226, 48, v234
	v_lshl_add_u64 v[96:97], v[94:95], 0, v[232:233]
	v_lshlrev_b64 v[212:213], 11, v[210:211]
	v_ashrrev_i32_e32 v227, 31, v226
	v_add_u32_e32 v222, 0x80, v234
	global_load_dwordx4 v[182:185], v[96:97], off
	global_load_dwordx4 v[178:181], v[96:97], off offset:256
	v_lshl_add_u64 v[96:97], v[94:95], 0, v[212:213]
	v_lshlrev_b64 v[228:229], 11, v[226:227]
	v_ashrrev_i32_e32 v223, 31, v222
	v_add_u32_e32 v218, 0x90, v234
	global_load_dwordx4 v[174:177], v[96:97], off
	global_load_dwordx4 v[170:173], v[96:97], off offset:256
	v_lshl_add_u64 v[96:97], v[94:95], 0, v[228:229]
	v_lshlrev_b64 v[224:225], 11, v[222:223]
	v_ashrrev_i32_e32 v219, 31, v218
	v_add_u32_e32 v214, 0xa0, v234
	v_add_u32_e32 v206, 0xb0, v234
	global_load_dwordx4 v[166:169], v[96:97], off
	global_load_dwordx4 v[162:165], v[96:97], off offset:256
	v_lshl_add_u64 v[96:97], v[94:95], 0, v[224:225]
	v_lshlrev_b64 v[220:221], 11, v[218:219]
	v_ashrrev_i32_e32 v215, 31, v214
	v_ashrrev_i32_e32 v207, 31, v206
	global_load_dwordx4 v[158:161], v[96:97], off
	global_load_dwordx4 v[150:153], v[96:97], off offset:256
	v_lshl_add_u64 v[96:97], v[94:95], 0, v[220:221]
	v_lshlrev_b64 v[216:217], 11, v[214:215]
	v_lshlrev_b64 v[208:209], 11, v[206:207]
	global_load_dwordx4 v[142:145], v[96:97], off
	global_load_dwordx4 v[138:141], v[96:97], off offset:256
	v_lshl_add_u64 v[96:97], v[94:95], 0, v[216:217]
	v_lshl_add_u64 v[94:95], v[94:95], 0, v[208:209]
	global_load_dwordx4 v[126:129], v[96:97], off
	global_load_dwordx4 v[114:117], v[96:97], off offset:256
	global_load_dwordx4 v[106:109], v[94:95], off
	s_nop 0
	global_load_dwordx4 v[94:97], v[94:95], off offset:256
	s_lshl_b32 s82, s25, 2
	s_ashr_i32 s83, s82, 31
	s_mov_b32 s31, 0xf800000
	s_lshl_b32 s76, s55, 2
	s_waitcnt vmcnt(14)
	v_lshlrev_b32_e32 v244, 16, v190
	v_and_b32_e32 v245, 0xffff0000, v190
	v_pk_fma_f32 v[154:155], v[154:155], 0.5, v[244:245] op_sel_hi:[1,0,1]
	v_lshlrev_b32_e32 v244, 16, v191
	v_and_b32_e32 v245, 0xffff0000, v191
	v_pk_fma_f32 v[156:157], v[156:157], 0.5, v[244:245] op_sel_hi:[1,0,1]
	v_lshlrev_b32_e32 v244, 16, v192
	v_and_b32_e32 v245, 0xffff0000, v192
	v_pk_fma_f32 v[146:147], v[146:147], 0.5, v[244:245] op_sel_hi:[1,0,1]
	v_lshlrev_b32_e32 v244, 16, v193
	v_and_b32_e32 v245, 0xffff0000, v193
	v_pk_fma_f32 v[148:149], v[148:149], 0.5, v[244:245] op_sel_hi:[1,0,1]
	v_cvt_pk_bf16_f32 v190, v154, v155
	v_pk_mul_f32 v[246:247], v[154:155], v[154:155]
	v_cvt_pk_bf16_f32 v191, v156, v157
	v_pk_fma_f32 v[246:247], v[156:157], v[156:157], v[246:247]
	v_cvt_pk_bf16_f32 v192, v146, v147
	v_pk_fma_f32 v[246:247], v[146:147], v[146:147], v[246:247]
	v_cvt_pk_bf16_f32 v193, v148, v149
	v_pk_fma_f32 v[246:247], v[148:149], v[148:149], v[246:247]
	v_lshl_add_u64 v[154:155], s[88:89], 0, v[238:239]
	v_lshl_add_u64 v[154:155], v[154:155], 0, v[236:237]
	global_store_dwordx4 v[154:155], v[190:193], off
	v_lshlrev_b32_e32 v244, 16, v186
	v_and_b32_e32 v245, 0xffff0000, v186
	v_pk_fma_f32 v[134:135], v[134:135], 0.5, v[244:245] op_sel_hi:[1,0,1]
	v_lshlrev_b32_e32 v244, 16, v187
	v_and_b32_e32 v245, 0xffff0000, v187
	v_pk_fma_f32 v[136:137], v[136:137], 0.5, v[244:245] op_sel_hi:[1,0,1]
	v_lshlrev_b32_e32 v244, 16, v188
	v_and_b32_e32 v245, 0xffff0000, v188
	v_pk_fma_f32 v[130:131], v[130:131], 0.5, v[244:245] op_sel_hi:[1,0,1]
	v_lshlrev_b32_e32 v244, 16, v189
	v_and_b32_e32 v245, 0xffff0000, v189
	v_pk_fma_f32 v[132:133], v[132:133], 0.5, v[244:245] op_sel_hi:[1,0,1]
	v_cvt_pk_bf16_f32 v186, v134, v135
	v_pk_fma_f32 v[246:247], v[134:135], v[134:135], v[246:247]
	v_cvt_pk_bf16_f32 v187, v136, v137
	v_pk_fma_f32 v[246:247], v[136:137], v[136:137], v[246:247]
	v_cvt_pk_bf16_f32 v188, v130, v131
	v_pk_fma_f32 v[246:247], v[130:131], v[130:131], v[246:247]
	v_cvt_pk_bf16_f32 v189, v132, v133
	v_pk_fma_f32 v[246:247], v[132:133], v[132:133], v[246:247]
	global_store_dwordx4 v[154:155], v[186:189], off offset:256
	v_add_f32_e32 v246, v246, v247
	v_mov_b32_e32 v146, v246
	v_lshlrev_b64 v[156:157], 6, v[234:235]
	v_lshl_add_u64 v[156:157], s[38:39], 0, v[156:157]
	v_permlane16_swap_b32_e32 v146, v246
	v_add_f32_e32 v246, v146, v246
	v_mov_b32_e32 v146, v246
	v_lshl_add_u64 v[156:157], s[82:83], 2, v[156:157]
	v_lshl_add_u64 v[156:157], v[156:157], 0, s[76:77]
	v_permlane32_swap_b32_e32 v146, v246
	v_add_f32_e32 v246, v146, v246
	s_and_saveexec_b64 s[48:49], vcc
	global_store_dword v[156:157], v246, off
	s_or_b64 exec, exec, s[48:49]
	s_waitcnt vmcnt(15)
	v_lshlrev_b32_e32 v244, 16, v182
	v_and_b32_e32 v245, 0xffff0000, v182
	v_pk_fma_f32 v[122:123], v[122:123], 0.5, v[244:245] op_sel_hi:[1,0,1]
	v_lshlrev_b32_e32 v244, 16, v183
	v_and_b32_e32 v245, 0xffff0000, v183
	v_pk_fma_f32 v[124:125], v[124:125], 0.5, v[244:245] op_sel_hi:[1,0,1]
	v_lshlrev_b32_e32 v244, 16, v184
	v_and_b32_e32 v245, 0xffff0000, v184
	v_pk_fma_f32 v[118:119], v[118:119], 0.5, v[244:245] op_sel_hi:[1,0,1]
	v_lshlrev_b32_e32 v244, 16, v185
	v_and_b32_e32 v245, 0xffff0000, v185
	v_pk_fma_f32 v[120:121], v[120:121], 0.5, v[244:245] op_sel_hi:[1,0,1]
	v_cvt_pk_bf16_f32 v182, v122, v123
	v_pk_mul_f32 v[246:247], v[122:123], v[122:123]
	v_cvt_pk_bf16_f32 v183, v124, v125
	v_pk_fma_f32 v[246:247], v[124:125], v[124:125], v[246:247]
	v_cvt_pk_bf16_f32 v184, v118, v119
	v_pk_fma_f32 v[246:247], v[118:119], v[118:119], v[246:247]
	v_cvt_pk_bf16_f32 v185, v120, v121
	v_pk_fma_f32 v[246:247], v[120:121], v[120:121], v[246:247]
	v_lshl_add_u64 v[122:123], s[88:89], 0, v[232:233]
	v_lshl_add_u64 v[122:123], v[122:123], 0, v[236:237]
	global_store_dwordx4 v[122:123], v[182:185], off
	v_lshlrev_b32_e32 v244, 16, v178
	v_and_b32_e32 v245, 0xffff0000, v178
	v_pk_fma_f32 v[110:111], v[110:111], 0.5, v[244:245] op_sel_hi:[1,0,1]
	v_lshlrev_b32_e32 v244, 16, v179
	v_and_b32_e32 v245, 0xffff0000, v179
	v_pk_fma_f32 v[112:113], v[112:113], 0.5, v[244:245] op_sel_hi:[1,0,1]
	v_lshlrev_b32_e32 v244, 16, v180
	v_and_b32_e32 v245, 0xffff0000, v180
	v_pk_fma_f32 v[102:103], v[102:103], 0.5, v[244:245] op_sel_hi:[1,0,1]
	v_lshlrev_b32_e32 v244, 16, v181
	v_and_b32_e32 v245, 0xffff0000, v181
	v_pk_fma_f32 v[104:105], v[104:105], 0.5, v[244:245] op_sel_hi:[1,0,1]
	v_cvt_pk_bf16_f32 v178, v110, v111
	v_pk_fma_f32 v[246:247], v[110:111], v[110:111], v[246:247]
	v_cvt_pk_bf16_f32 v179, v112, v113
	v_pk_fma_f32 v[246:247], v[112:113], v[112:113], v[246:247]
	v_cvt_pk_bf16_f32 v180, v102, v103
	v_pk_fma_f32 v[246:247], v[102:103], v[102:103], v[246:247]
	v_cvt_pk_bf16_f32 v181, v104, v105
	v_pk_fma_f32 v[246:247], v[104:105], v[104:105], v[246:247]
	global_store_dwordx4 v[122:123], v[178:181], off offset:256
	v_add_f32_e32 v246, v246, v247
	v_mov_b32_e32 v118, v246
	v_lshlrev_b64 v[124:125], 6, v[230:231]
	v_lshl_add_u64 v[124:125], s[38:39], 0, v[124:125]
	v_permlane16_swap_b32_e32 v118, v246
	v_add_f32_e32 v246, v118, v246
	v_mov_b32_e32 v118, v246
	v_lshl_add_u64 v[124:125], s[82:83], 2, v[124:125]
	v_lshl_add_u64 v[124:125], v[124:125], 0, s[76:77]
	v_permlane32_swap_b32_e32 v118, v246
	v_add_f32_e32 v246, v118, v246
	s_and_saveexec_b64 s[48:49], vcc
	global_store_dword v[124:125], v246, off
	s_or_b64 exec, exec, s[48:49]
	s_waitcnt vmcnt(16)
	v_lshlrev_b32_e32 v244, 16, v174
	v_and_b32_e32 v245, 0xffff0000, v174
	v_pk_fma_f32 v[98:99], v[98:99], 0.5, v[244:245] op_sel_hi:[1,0,1]
	v_lshlrev_b32_e32 v244, 16, v175
	v_and_b32_e32 v245, 0xffff0000, v175
	v_pk_fma_f32 v[100:101], v[100:101], 0.5, v[244:245] op_sel_hi:[1,0,1]
	v_lshlrev_b32_e32 v244, 16, v176
	v_and_b32_e32 v245, 0xffff0000, v176
	v_pk_fma_f32 v[90:91], v[90:91], 0.5, v[244:245] op_sel_hi:[1,0,1]
	v_lshlrev_b32_e32 v244, 16, v177
	v_and_b32_e32 v245, 0xffff0000, v177
	v_pk_fma_f32 v[92:93], v[92:93], 0.5, v[244:245] op_sel_hi:[1,0,1]
	v_cvt_pk_bf16_f32 v174, v98, v99
	v_pk_mul_f32 v[246:247], v[98:99], v[98:99]
	v_cvt_pk_bf16_f32 v175, v100, v101
	v_pk_fma_f32 v[246:247], v[100:101], v[100:101], v[246:247]
	v_cvt_pk_bf16_f32 v176, v90, v91
	v_pk_fma_f32 v[246:247], v[90:91], v[90:91], v[246:247]
	v_cvt_pk_bf16_f32 v177, v92, v93
	v_pk_fma_f32 v[246:247], v[92:93], v[92:93], v[246:247]
	v_lshl_add_u64 v[98:99], s[88:89], 0, v[212:213]
	v_lshl_add_u64 v[98:99], v[98:99], 0, v[236:237]
	global_store_dwordx4 v[98:99], v[174:177], off
	v_lshlrev_b32_e32 v244, 16, v170
	v_and_b32_e32 v245, 0xffff0000, v170
	v_pk_fma_f32 v[86:87], v[86:87], 0.5, v[244:245] op_sel_hi:[1,0,1]
	v_lshlrev_b32_e32 v244, 16, v171
	v_and_b32_e32 v245, 0xffff0000, v171
	v_pk_fma_f32 v[88:89], v[88:89], 0.5, v[244:245] op_sel_hi:[1,0,1]
	v_lshlrev_b32_e32 v244, 16, v172
	v_and_b32_e32 v245, 0xffff0000, v172
	v_pk_fma_f32 v[82:83], v[82:83], 0.5, v[244:245] op_sel_hi:[1,0,1]
	v_lshlrev_b32_e32 v244, 16, v173
	v_and_b32_e32 v245, 0xffff0000, v173
	v_pk_fma_f32 v[84:85], v[84:85], 0.5, v[244:245] op_sel_hi:[1,0,1]
	v_cvt_pk_bf16_f32 v170, v86, v87
	v_pk_fma_f32 v[246:247], v[86:87], v[86:87], v[246:247]
	v_cvt_pk_bf16_f32 v171, v88, v89
	v_pk_fma_f32 v[246:247], v[88:89], v[88:89], v[246:247]
	v_cvt_pk_bf16_f32 v172, v82, v83
	v_pk_fma_f32 v[246:247], v[82:83], v[82:83], v[246:247]
	v_cvt_pk_bf16_f32 v173, v84, v85
	v_pk_fma_f32 v[246:247], v[84:85], v[84:85], v[246:247]
	global_store_dwordx4 v[98:99], v[170:173], off offset:256
	v_add_f32_e32 v246, v246, v247
	v_mov_b32_e32 v90, v246
	v_lshlrev_b64 v[100:101], 6, v[210:211]
	v_lshl_add_u64 v[100:101], s[38:39], 0, v[100:101]
	v_permlane16_swap_b32_e32 v90, v246
	v_add_f32_e32 v246, v90, v246
	v_mov_b32_e32 v90, v246
	v_lshl_add_u64 v[100:101], s[82:83], 2, v[100:101]
	v_lshl_add_u64 v[100:101], v[100:101], 0, s[76:77]
	v_permlane32_swap_b32_e32 v90, v246
	v_add_f32_e32 v246, v90, v246
	s_and_saveexec_b64 s[48:49], vcc
	global_store_dword v[100:101], v246, off
	s_or_b64 exec, exec, s[48:49]
	s_waitcnt vmcnt(17)
	v_lshlrev_b32_e32 v244, 16, v166
	v_and_b32_e32 v245, 0xffff0000, v166
	v_pk_fma_f32 v[78:79], v[78:79], 0.5, v[244:245] op_sel_hi:[1,0,1]
	v_lshlrev_b32_e32 v244, 16, v167
	v_and_b32_e32 v245, 0xffff0000, v167
	v_pk_fma_f32 v[80:81], v[80:81], 0.5, v[244:245] op_sel_hi:[1,0,1]
	v_lshlrev_b32_e32 v244, 16, v168
	v_and_b32_e32 v245, 0xffff0000, v168
	v_pk_fma_f32 v[74:75], v[74:75], 0.5, v[244:245] op_sel_hi:[1,0,1]
	v_lshlrev_b32_e32 v244, 16, v169
	v_and_b32_e32 v245, 0xffff0000, v169
	v_pk_fma_f32 v[76:77], v[76:77], 0.5, v[244:245] op_sel_hi:[1,0,1]
	v_cvt_pk_bf16_f32 v166, v78, v79
	v_pk_mul_f32 v[246:247], v[78:79], v[78:79]
	v_cvt_pk_bf16_f32 v167, v80, v81
	v_pk_fma_f32 v[246:247], v[80:81], v[80:81], v[246:247]
	v_cvt_pk_bf16_f32 v168, v74, v75
	v_pk_fma_f32 v[246:247], v[74:75], v[74:75], v[246:247]
	v_cvt_pk_bf16_f32 v169, v76, v77
	v_pk_fma_f32 v[246:247], v[76:77], v[76:77], v[246:247]
	v_lshl_add_u64 v[78:79], s[88:89], 0, v[228:229]
	v_lshl_add_u64 v[78:79], v[78:79], 0, v[236:237]
	global_store_dwordx4 v[78:79], v[166:169], off
	v_lshlrev_b32_e32 v244, 16, v162
	v_and_b32_e32 v245, 0xffff0000, v162
	v_pk_fma_f32 v[70:71], v[70:71], 0.5, v[244:245] op_sel_hi:[1,0,1]
	v_lshlrev_b32_e32 v244, 16, v163
	v_and_b32_e32 v245, 0xffff0000, v163
	v_pk_fma_f32 v[72:73], v[72:73], 0.5, v[244:245] op_sel_hi:[1,0,1]
	v_lshlrev_b32_e32 v244, 16, v164
	v_and_b32_e32 v245, 0xffff0000, v164
	v_pk_fma_f32 v[66:67], v[66:67], 0.5, v[244:245] op_sel_hi:[1,0,1]
	v_lshlrev_b32_e32 v244, 16, v165
	v_and_b32_e32 v245, 0xffff0000, v165
	v_pk_fma_f32 v[68:69], v[68:69], 0.5, v[244:245] op_sel_hi:[1,0,1]
	v_cvt_pk_bf16_f32 v162, v70, v71
	v_pk_fma_f32 v[246:247], v[70:71], v[70:71], v[246:247]
	v_cvt_pk_bf16_f32 v163, v72, v73
	v_pk_fma_f32 v[246:247], v[72:73], v[72:73], v[246:247]
	v_cvt_pk_bf16_f32 v164, v66, v67
	v_pk_fma_f32 v[246:247], v[66:67], v[66:67], v[246:247]
	v_cvt_pk_bf16_f32 v165, v68, v69
	v_pk_fma_f32 v[246:247], v[68:69], v[68:69], v[246:247]
	global_store_dwordx4 v[78:79], v[162:165], off offset:256
	v_add_f32_e32 v246, v246, v247
	v_mov_b32_e32 v74, v246
	v_lshlrev_b64 v[80:81], 6, v[226:227]
	v_lshl_add_u64 v[80:81], s[38:39], 0, v[80:81]
	v_permlane16_swap_b32_e32 v74, v246
	v_add_f32_e32 v246, v74, v246
	v_mov_b32_e32 v74, v246
	v_lshl_add_u64 v[80:81], s[82:83], 2, v[80:81]
	v_lshl_add_u64 v[80:81], v[80:81], 0, s[76:77]
	v_permlane32_swap_b32_e32 v74, v246
	v_add_f32_e32 v246, v74, v246
	s_and_saveexec_b64 s[48:49], vcc
	global_store_dword v[80:81], v246, off
	s_or_b64 exec, exec, s[48:49]
	s_waitcnt vmcnt(18)
	v_lshlrev_b32_e32 v244, 16, v158
	v_and_b32_e32 v245, 0xffff0000, v158
	v_pk_fma_f32 v[62:63], v[62:63], 0.5, v[244:245] op_sel_hi:[1,0,1]
	v_lshlrev_b32_e32 v244, 16, v159
	v_and_b32_e32 v245, 0xffff0000, v159
	v_pk_fma_f32 v[64:65], v[64:65], 0.5, v[244:245] op_sel_hi:[1,0,1]
	v_lshlrev_b32_e32 v244, 16, v160
	v_and_b32_e32 v245, 0xffff0000, v160
	v_pk_fma_f32 v[58:59], v[58:59], 0.5, v[244:245] op_sel_hi:[1,0,1]
	v_lshlrev_b32_e32 v244, 16, v161
	v_and_b32_e32 v245, 0xffff0000, v161
	v_pk_fma_f32 v[60:61], v[60:61], 0.5, v[244:245] op_sel_hi:[1,0,1]
	v_cvt_pk_bf16_f32 v158, v62, v63
	v_pk_mul_f32 v[246:247], v[62:63], v[62:63]
	v_cvt_pk_bf16_f32 v159, v64, v65
	v_pk_fma_f32 v[246:247], v[64:65], v[64:65], v[246:247]
	v_cvt_pk_bf16_f32 v160, v58, v59
	v_pk_fma_f32 v[246:247], v[58:59], v[58:59], v[246:247]
	v_cvt_pk_bf16_f32 v161, v60, v61
	v_pk_fma_f32 v[246:247], v[60:61], v[60:61], v[246:247]
	v_lshl_add_u64 v[62:63], s[88:89], 0, v[224:225]
	v_lshl_add_u64 v[62:63], v[62:63], 0, v[236:237]
	global_store_dwordx4 v[62:63], v[158:161], off
	v_lshlrev_b32_e32 v244, 16, v150
	v_and_b32_e32 v245, 0xffff0000, v150
	v_pk_fma_f32 v[54:55], v[54:55], 0.5, v[244:245] op_sel_hi:[1,0,1]
	v_lshlrev_b32_e32 v244, 16, v151
	v_and_b32_e32 v245, 0xffff0000, v151
	v_pk_fma_f32 v[56:57], v[56:57], 0.5, v[244:245] op_sel_hi:[1,0,1]
	v_lshlrev_b32_e32 v244, 16, v152
	v_and_b32_e32 v245, 0xffff0000, v152
	v_pk_fma_f32 v[50:51], v[50:51], 0.5, v[244:245] op_sel_hi:[1,0,1]
	v_lshlrev_b32_e32 v244, 16, v153
	v_and_b32_e32 v245, 0xffff0000, v153
	v_pk_fma_f32 v[52:53], v[52:53], 0.5, v[244:245] op_sel_hi:[1,0,1]
	v_cvt_pk_bf16_f32 v150, v54, v55
	v_pk_fma_f32 v[246:247], v[54:55], v[54:55], v[246:247]
	v_cvt_pk_bf16_f32 v151, v56, v57
	v_pk_fma_f32 v[246:247], v[56:57], v[56:57], v[246:247]
	v_cvt_pk_bf16_f32 v152, v50, v51
	v_pk_fma_f32 v[246:247], v[50:51], v[50:51], v[246:247]
	v_cvt_pk_bf16_f32 v153, v52, v53
	v_pk_fma_f32 v[246:247], v[52:53], v[52:53], v[246:247]
	global_store_dwordx4 v[62:63], v[150:153], off offset:256
	v_add_f32_e32 v246, v246, v247
	v_mov_b32_e32 v58, v246
	v_lshlrev_b64 v[64:65], 6, v[222:223]
	v_lshl_add_u64 v[64:65], s[38:39], 0, v[64:65]
	v_permlane16_swap_b32_e32 v58, v246
	v_add_f32_e32 v246, v58, v246
	v_mov_b32_e32 v58, v246
	v_lshl_add_u64 v[64:65], s[82:83], 2, v[64:65]
	v_lshl_add_u64 v[64:65], v[64:65], 0, s[76:77]
	v_permlane32_swap_b32_e32 v58, v246
	v_add_f32_e32 v246, v58, v246
	s_and_saveexec_b64 s[48:49], vcc
	global_store_dword v[64:65], v246, off
	s_or_b64 exec, exec, s[48:49]
	s_waitcnt vmcnt(19)
	v_lshlrev_b32_e32 v244, 16, v142
	v_and_b32_e32 v245, 0xffff0000, v142
	v_pk_fma_f32 v[46:47], v[46:47], 0.5, v[244:245] op_sel_hi:[1,0,1]
	v_lshlrev_b32_e32 v244, 16, v143
	v_and_b32_e32 v245, 0xffff0000, v143
	v_pk_fma_f32 v[48:49], v[48:49], 0.5, v[244:245] op_sel_hi:[1,0,1]
	v_lshlrev_b32_e32 v244, 16, v144
	v_and_b32_e32 v245, 0xffff0000, v144
	v_pk_fma_f32 v[42:43], v[42:43], 0.5, v[244:245] op_sel_hi:[1,0,1]
	v_lshlrev_b32_e32 v244, 16, v145
	v_and_b32_e32 v245, 0xffff0000, v145
	v_pk_fma_f32 v[44:45], v[44:45], 0.5, v[244:245] op_sel_hi:[1,0,1]
	v_cvt_pk_bf16_f32 v142, v46, v47
	v_pk_mul_f32 v[246:247], v[46:47], v[46:47]
	v_cvt_pk_bf16_f32 v143, v48, v49
	v_pk_fma_f32 v[246:247], v[48:49], v[48:49], v[246:247]
	v_cvt_pk_bf16_f32 v144, v42, v43
	v_pk_fma_f32 v[246:247], v[42:43], v[42:43], v[246:247]
	v_cvt_pk_bf16_f32 v145, v44, v45
	v_pk_fma_f32 v[246:247], v[44:45], v[44:45], v[246:247]
	v_lshl_add_u64 v[46:47], s[88:89], 0, v[220:221]
	v_lshl_add_u64 v[46:47], v[46:47], 0, v[236:237]
	global_store_dwordx4 v[46:47], v[142:145], off
	v_lshlrev_b32_e32 v244, 16, v138
	v_and_b32_e32 v245, 0xffff0000, v138
	v_pk_fma_f32 v[38:39], v[38:39], 0.5, v[244:245] op_sel_hi:[1,0,1]
	v_lshlrev_b32_e32 v244, 16, v139
	v_and_b32_e32 v245, 0xffff0000, v139
	v_pk_fma_f32 v[40:41], v[40:41], 0.5, v[244:245] op_sel_hi:[1,0,1]
	v_lshlrev_b32_e32 v244, 16, v140
	v_and_b32_e32 v245, 0xffff0000, v140
	v_pk_fma_f32 v[34:35], v[34:35], 0.5, v[244:245] op_sel_hi:[1,0,1]
	v_lshlrev_b32_e32 v244, 16, v141
	v_and_b32_e32 v245, 0xffff0000, v141
	v_pk_fma_f32 v[36:37], v[36:37], 0.5, v[244:245] op_sel_hi:[1,0,1]
	v_cvt_pk_bf16_f32 v138, v38, v39
	v_pk_fma_f32 v[246:247], v[38:39], v[38:39], v[246:247]
	v_cvt_pk_bf16_f32 v139, v40, v41
	v_pk_fma_f32 v[246:247], v[40:41], v[40:41], v[246:247]
	v_cvt_pk_bf16_f32 v140, v34, v35
	v_pk_fma_f32 v[246:247], v[34:35], v[34:35], v[246:247]
	v_cvt_pk_bf16_f32 v141, v36, v37
	v_pk_fma_f32 v[246:247], v[36:37], v[36:37], v[246:247]
	global_store_dwordx4 v[46:47], v[138:141], off offset:256
	v_add_f32_e32 v246, v246, v247
	v_mov_b32_e32 v42, v246
	v_lshlrev_b64 v[48:49], 6, v[218:219]
	v_lshl_add_u64 v[48:49], s[38:39], 0, v[48:49]
	v_permlane16_swap_b32_e32 v42, v246
	v_add_f32_e32 v246, v42, v246
	v_mov_b32_e32 v42, v246
	v_lshl_add_u64 v[48:49], s[82:83], 2, v[48:49]
	v_lshl_add_u64 v[48:49], v[48:49], 0, s[76:77]
	v_permlane32_swap_b32_e32 v42, v246
	v_add_f32_e32 v246, v42, v246
	s_and_saveexec_b64 s[48:49], vcc
	global_store_dword v[48:49], v246, off
	s_or_b64 exec, exec, s[48:49]
	s_waitcnt vmcnt(20)
	v_lshlrev_b32_e32 v244, 16, v126
	v_and_b32_e32 v245, 0xffff0000, v126
	v_pk_fma_f32 v[30:31], v[30:31], 0.5, v[244:245] op_sel_hi:[1,0,1]
	v_lshlrev_b32_e32 v244, 16, v127
	v_and_b32_e32 v245, 0xffff0000, v127
	v_pk_fma_f32 v[32:33], v[32:33], 0.5, v[244:245] op_sel_hi:[1,0,1]
	v_lshlrev_b32_e32 v244, 16, v128
	v_and_b32_e32 v245, 0xffff0000, v128
	v_pk_fma_f32 v[26:27], v[26:27], 0.5, v[244:245] op_sel_hi:[1,0,1]
	v_lshlrev_b32_e32 v244, 16, v129
	v_and_b32_e32 v245, 0xffff0000, v129
	v_pk_fma_f32 v[28:29], v[28:29], 0.5, v[244:245] op_sel_hi:[1,0,1]
	v_cvt_pk_bf16_f32 v126, v30, v31
	v_pk_mul_f32 v[246:247], v[30:31], v[30:31]
	v_cvt_pk_bf16_f32 v127, v32, v33
	v_pk_fma_f32 v[246:247], v[32:33], v[32:33], v[246:247]
	v_cvt_pk_bf16_f32 v128, v26, v27
	v_pk_fma_f32 v[246:247], v[26:27], v[26:27], v[246:247]
	v_cvt_pk_bf16_f32 v129, v28, v29
	v_pk_fma_f32 v[246:247], v[28:29], v[28:29], v[246:247]
	v_lshl_add_u64 v[30:31], s[88:89], 0, v[216:217]
	v_lshl_add_u64 v[30:31], v[30:31], 0, v[236:237]
	global_store_dwordx4 v[30:31], v[126:129], off
	v_lshlrev_b32_e32 v244, 16, v114
	v_and_b32_e32 v245, 0xffff0000, v114
	v_pk_fma_f32 v[22:23], v[22:23], 0.5, v[244:245] op_sel_hi:[1,0,1]
	v_lshlrev_b32_e32 v244, 16, v115
	v_and_b32_e32 v245, 0xffff0000, v115
	v_pk_fma_f32 v[24:25], v[24:25], 0.5, v[244:245] op_sel_hi:[1,0,1]
	v_lshlrev_b32_e32 v244, 16, v116
	v_and_b32_e32 v245, 0xffff0000, v116
	v_pk_fma_f32 v[18:19], v[18:19], 0.5, v[244:245] op_sel_hi:[1,0,1]
	v_lshlrev_b32_e32 v244, 16, v117
	v_and_b32_e32 v245, 0xffff0000, v117
	v_pk_fma_f32 v[20:21], v[20:21], 0.5, v[244:245] op_sel_hi:[1,0,1]
	v_cvt_pk_bf16_f32 v114, v22, v23
	v_pk_fma_f32 v[246:247], v[22:23], v[22:23], v[246:247]
	v_cvt_pk_bf16_f32 v115, v24, v25
	v_pk_fma_f32 v[246:247], v[24:25], v[24:25], v[246:247]
	v_cvt_pk_bf16_f32 v116, v18, v19
	v_pk_fma_f32 v[246:247], v[18:19], v[18:19], v[246:247]
	v_cvt_pk_bf16_f32 v117, v20, v21
	v_pk_fma_f32 v[246:247], v[20:21], v[20:21], v[246:247]
	global_store_dwordx4 v[30:31], v[114:117], off offset:256
	v_add_f32_e32 v246, v246, v247
	v_mov_b32_e32 v26, v246
	v_lshlrev_b64 v[32:33], 6, v[214:215]
	v_lshl_add_u64 v[32:33], s[38:39], 0, v[32:33]
	v_permlane16_swap_b32_e32 v26, v246
	v_add_f32_e32 v246, v26, v246
	v_mov_b32_e32 v26, v246
	v_lshl_add_u64 v[32:33], s[82:83], 2, v[32:33]
	v_lshl_add_u64 v[32:33], v[32:33], 0, s[76:77]
	v_permlane32_swap_b32_e32 v26, v246
	v_add_f32_e32 v246, v26, v246
	s_and_saveexec_b64 s[48:49], vcc
	global_store_dword v[32:33], v246, off
	s_or_b64 exec, exec, s[48:49]
	s_waitcnt vmcnt(21)
	v_lshlrev_b32_e32 v244, 16, v106
	v_and_b32_e32 v245, 0xffff0000, v106
	v_pk_fma_f32 v[14:15], v[14:15], 0.5, v[244:245] op_sel_hi:[1,0,1]
	v_lshlrev_b32_e32 v244, 16, v107
	v_and_b32_e32 v245, 0xffff0000, v107
	v_pk_fma_f32 v[16:17], v[16:17], 0.5, v[244:245] op_sel_hi:[1,0,1]
	v_lshlrev_b32_e32 v244, 16, v108
	v_and_b32_e32 v245, 0xffff0000, v108
	v_pk_fma_f32 v[10:11], v[10:11], 0.5, v[244:245] op_sel_hi:[1,0,1]
	v_lshlrev_b32_e32 v244, 16, v109
	v_and_b32_e32 v245, 0xffff0000, v109
	v_pk_fma_f32 v[12:13], v[12:13], 0.5, v[244:245] op_sel_hi:[1,0,1]
	v_cvt_pk_bf16_f32 v106, v14, v15
	v_pk_mul_f32 v[246:247], v[14:15], v[14:15]
	v_cvt_pk_bf16_f32 v107, v16, v17
	v_pk_fma_f32 v[246:247], v[16:17], v[16:17], v[246:247]
	v_cvt_pk_bf16_f32 v108, v10, v11
	v_pk_fma_f32 v[246:247], v[10:11], v[10:11], v[246:247]
	v_cvt_pk_bf16_f32 v109, v12, v13
	v_pk_fma_f32 v[246:247], v[12:13], v[12:13], v[246:247]
	v_lshl_add_u64 v[14:15], s[88:89], 0, v[208:209]
	v_lshl_add_u64 v[14:15], v[14:15], 0, v[236:237]
	global_store_dwordx4 v[14:15], v[106:109], off
	v_lshlrev_b32_e32 v244, 16, v94
	v_and_b32_e32 v245, 0xffff0000, v94
	v_pk_fma_f32 v[6:7], v[6:7], 0.5, v[244:245] op_sel_hi:[1,0,1]
	v_lshlrev_b32_e32 v244, 16, v95
	v_and_b32_e32 v245, 0xffff0000, v95
	v_pk_fma_f32 v[8:9], v[8:9], 0.5, v[244:245] op_sel_hi:[1,0,1]
	v_lshlrev_b32_e32 v244, 16, v96
	v_and_b32_e32 v245, 0xffff0000, v96
	v_pk_fma_f32 v[2:3], v[2:3], 0.5, v[244:245] op_sel_hi:[1,0,1]
	v_lshlrev_b32_e32 v244, 16, v97
	v_and_b32_e32 v245, 0xffff0000, v97
	v_pk_fma_f32 v[4:5], v[4:5], 0.5, v[244:245] op_sel_hi:[1,0,1]
	v_cvt_pk_bf16_f32 v94, v6, v7
	v_pk_fma_f32 v[246:247], v[6:7], v[6:7], v[246:247]
	v_cvt_pk_bf16_f32 v95, v8, v9
	v_pk_fma_f32 v[246:247], v[8:9], v[8:9], v[246:247]
	v_cvt_pk_bf16_f32 v96, v2, v3
	v_pk_fma_f32 v[246:247], v[2:3], v[2:3], v[246:247]
	v_cvt_pk_bf16_f32 v97, v4, v5
	v_pk_fma_f32 v[246:247], v[4:5], v[4:5], v[246:247]
	global_store_dwordx4 v[14:15], v[94:97], off offset:256
	v_add_f32_e32 v246, v246, v247
	v_mov_b32_e32 v10, v246
	v_lshlrev_b64 v[16:17], 6, v[206:207]
	v_lshl_add_u64 v[16:17], s[38:39], 0, v[16:17]
	v_permlane16_swap_b32_e32 v10, v246
	v_add_f32_e32 v246, v10, v246
	v_mov_b32_e32 v10, v246
	v_lshl_add_u64 v[16:17], s[82:83], 2, v[16:17]
	v_lshl_add_u64 v[16:17], v[16:17], 0, s[76:77]
	v_permlane32_swap_b32_e32 v10, v246
	v_add_f32_e32 v246, v10, v246
	s_and_saveexec_b64 s[48:49], vcc
	global_store_dword v[16:17], v246, off
	s_or_b64 exec, exec, s[48:49]
	s_andn2_b64 vcc, exec, s[40:41]
	s_mov_b64 s[40:41], -1
	s_cbranch_vccnz .LBB0_263
	s_andn2_b64 vcc, exec, s[0:1]
	s_cbranch_vccnz .LBB0_262
	s_barrier
	s_branch .LBB0_262
